# NSA top-k v2: 4 DPP steps + v_readlane/s_max for the cross-row max, selection bits derived after the loop, SGPR loop counter; plus paired importance RMWs
# speedup vs baseline: 1.0057x; 1.0057x over previous
; template <int CTRL> __device__ __forceinline__ unsigned dppu(unsigned x) { return (unsigned)__builtin_amdgcn_mov_dpp((int)x, CTRL, 0xf, 0xf, true); }
; __device__ __forceinline__ unsigned wave_max_u32(unsigned x) {
;     x = max(x, dppu<0xB1>(x)); x = max(x, dppu<0x4E>(x)); x = max(x, dppu<0x141>(x)); x = max(x, dppu<0x140>(x));
;     auto s = __builtin_amdgcn_permlane16_swap(x, x, false, false); x = max((unsigned)s[0], (unsigned)s[1]);
;     auto t = __builtin_amdgcn_permlane32_swap(x, x, false, false); return max((unsigned)t[0], (unsigned)t[1]);
; }
; __device__ __forceinline__ void nsa_block(LAS unsigned char* lds, int b, int g, int t0b, int tid) {
;     ...
;             unsigned sb = 0u;
;             for (int it = 0; it < nsel; ++it) {
;                 const unsigned best = wave_max_u32(max(max(k0, k1), max(k2, k3)));
;                 const int bi = 255 - (int)(best & 0xffu);
;                 if ((bi & 63) == lane) { const int ii = bi >> 6; sb |= 1u << ii; if (ii == 0) k0 = 0u; else if (ii == 1) k1 = 0u; else if (ii == 2) k2 = 0u; else k3 = 0u; }
;             }
.LBB0_965:
	v_readfirstlane_b32 s98, v57
	v_mov_b32_e32 v250, v59
	v_mov_b32_e32 v251, v58
	v_mov_b32_e32 v252, v61
	v_mov_b32_e32 v253, v60
.Ltopk_it:
	v_max_u32_e32 v64, v61, v60
	v_max3_u32 v64, v59, v58, v64
	s_nop 1
	v_max_u32_dpp v64, v64, v64 quad_perm:[1,0,3,2] row_mask:0xf bank_mask:0xf bound_ctrl:1
	s_nop 1
	v_max_u32_dpp v64, v64, v64 quad_perm:[2,3,0,1] row_mask:0xf bank_mask:0xf bound_ctrl:1
	s_nop 1
	v_max_u32_dpp v64, v64, v64 row_half_mirror row_mask:0xf bank_mask:0xf bound_ctrl:1
	s_nop 1
	v_max_u32_dpp v64, v64, v64 row_mirror row_mask:0xf bank_mask:0xf bound_ctrl:1
	s_nop 0
	v_readlane_b32 s60, v64, 0
	v_readlane_b32 s61, v64, 16
	v_readlane_b32 s62, v64, 32
	v_readlane_b32 s63, v64, 48
	s_max_u32 s60, s60, s61
	s_max_u32 s62, s62, s63
	s_max_u32 s60, s60, s62
	v_cmp_eq_u32_e64 s[62:63], v59, s60
	v_cmp_eq_u32_e64 s[64:65], v58, s60
	v_cmp_eq_u32_e64 s[66:67], v61, s60
	v_cmp_eq_u32_e64 s[68:69], v60, s60
	v_cndmask_b32_e64 v59, v59, 0, s[62:63]
	v_cndmask_b32_e64 v58, v58, 0, s[64:65]
	v_cndmask_b32_e64 v61, v61, 0, s[66:67]
	v_cndmask_b32_e64 v60, v60, 0, s[68:69]
	s_sub_u32 s98, s98, 1
	s_cmp_lg_u32 s98, 0
	s_cbranch_scc1 .Ltopk_it
	v_cmp_ne_u32_e64 s[62:63], v59, v250
	v_cmp_ne_u32_e64 s[64:65], v58, v251
	v_cmp_ne_u32_e64 s[66:67], v61, v252
	v_cmp_ne_u32_e64 s[68:69], v60, v253
	v_cndmask_b32_e64 v65, 0, 1, s[62:63]
	v_cndmask_b32_e64 v66, 0, 2, s[64:65]
	v_cndmask_b32_e64 v62, 0, 4, s[66:67]
	v_cndmask_b32_e64 v67, 0, 8, s[68:69]
	v_or3_b32 v62, v62, v65, v66
	v_or_b32_e32 v62, v62, v67
